# grid barrier: after its cache invalidate, wave 1 streams the first 8 KB of the next phase's code through LDS-DMA so the instruction fetches that follow the release hit L2
# speedup vs baseline: 1.0112x; 1.0089x over previous
; __device__ __forceinline__ unsigned xb_ld(unsigned* p)              { return __hip_atomic_load(p, __ATOMIC_RELAXED, __HIP_MEMORY_SCOPE_AGENT); }
; __device__ __forceinline__ unsigned xb_add(unsigned* p, unsigned v) { return __hip_atomic_fetch_add(p, v, __ATOMIC_RELAXED, __HIP_MEMORY_SCOPE_AGENT); }
; #define XB_SPIN(cond, bar) do { unsigned _sp = 0; while (cond) { __builtin_amdgcn_s_sleep(1); \
;     if ((++_sp & 255u) == 0u) { if (xb_ld(&(bar)[XB_TMO])) break; if (_sp > XB_SPIN_CAP) { atomicAdd(&(bar)[XB_TMO], 1u); break; } } } } while (0)
; __device__ __forceinline__ void xcd_barrier(const XcdBarrier& b) {
;     asm volatile("s_waitcnt vmcnt(0)" ::: "memory");
;     __syncthreads();
;     if (threadIdx.x == 0) {
;         unsigned* bar = b.bar;
;         __builtin_amdgcn_s_waitcnt(0);
;         unsigned nloc = b.st[0], nx = b.st[1];
;         if (nloc == 0u) { xcd_barrier_complete(bar, b.x, nloc, nx); b.st[0] = nloc; b.st[1] = nx; }
;         const unsigned old = xb_add(&bar[XB_XSUB(b.x)], 1u);
;         const unsigned gen = old / nloc;
;         if (old + 1u == (gen + 1u) * nloc) {
;             __builtin_amdgcn_fence(__ATOMIC_RELEASE, "agent");
;             asm volatile("s_waitcnt vmcnt(0)" ::: "memory");
;             const unsigned og = xb_add(&bar[XB_TOP], 1u);
;             const unsigned tg = og / nx;
;             if (og + 1u == (tg + 1u) * nx) xb_add(&bar[XB_TOPGEN], 1u);
;             else XB_SPIN(xb_ld(&bar[XB_TOPGEN]) == tg, bar);
;             __builtin_amdgcn_fence(__ATOMIC_ACQUIRE, "agent");
;             xb_add(&bar[XB_XGEN(b.x)], 1u);
;             asm volatile("s_waitcnt vmcnt(0)" ::: "memory");
;         } else {
;             XB_SPIN(xb_ld(&bar[XB_XGEN(b.x)]) == gen, bar);
;             __builtin_amdgcn_fence(__ATOMIC_ACQUIRE, "agent");
;             asm volatile("s_waitcnt vmcnt(0)" ::: "memory");
;         }
;     }
;     __syncthreads();
.Linit_done:
	s_or_b64 exec, exec, s[4:5]
	s_waitcnt vmcnt(0)
	s_waitcnt lgkmcnt(0)
	s_barrier
	v_readfirstlane_b32 s2, v152
	s_cmp_lg_u32 s2, 64
	s_cbranch_scc1 .Leinv_skip_0
	buffer_inv sc1
	s_waitcnt vmcnt(0)
	s_getpc_b64 s[2:3]
.Lwarm_pc_0:
	s_add_u32 s2, s2, .LBB0_115-.Lwarm_pc_0
	s_addc_u32 s3, s3, 0
	v_and_b32_e32 v0, 63, v152
	v_lshlrev_b32_e32 v0, 4, v0
	v_mov_b32_e32 v1, 0
	v_lshl_add_u64 v[0:1], s[2:3], 0, v[0:1]
	s_mov_b64 s[2:3], 0x400
	s_mov_b32 s8, 0
.Lwarm_loop_0:
	s_mov_b32 m0, s8
	s_nop 0
	global_load_lds_dwordx4 v[0:1], off
	v_lshl_add_u64 v[0:1], v[0:1], 0, s[2:3]
	s_add_u32 s8, s8, 0x400
	s_cmp_lt_u32 s8, 0x2000
	s_cbranch_scc1 .Lwarm_loop_0
	s_waitcnt vmcnt(0)

; __device__ __forceinline__ void xcd_barrier(const XcdBarrier& b) {
;     asm volatile("s_waitcnt vmcnt(0)" ::: "memory");
;     __syncthreads();
.LBB0_296:
	s_waitcnt vmcnt(0)
	s_waitcnt vmcnt(0)
	s_barrier
	v_readfirstlane_b32 s2, v152
	s_cmp_lg_u32 s2, 64
	s_cbranch_scc1 .Leinv_skip_1
	buffer_inv sc1
	s_waitcnt vmcnt(0)
	s_getpc_b64 s[2:3]

; __device__ __forceinline__ void xcd_barrier(const XcdBarrier& b) {
;     asm volatile("s_waitcnt vmcnt(0)" ::: "memory");
;     __syncthreads();
.LBB0_395:
	s_waitcnt vmcnt(0)
	s_waitcnt lgkmcnt(0)
	s_barrier
	v_readfirstlane_b32 s2, v152
	s_cmp_lg_u32 s2, 64
	s_cbranch_scc1 .Leinv_skip_2
	buffer_inv sc1
	s_waitcnt vmcnt(0)
	s_getpc_b64 s[2:3]

; __device__ __forceinline__ void xcd_barrier(const XcdBarrier& b) {
;     asm volatile("s_waitcnt vmcnt(0)" ::: "memory");
;     __syncthreads();
.LBB0_977:
	s_waitcnt vmcnt(0)
	s_barrier
	v_readfirstlane_b32 s2, v152
	s_cmp_lg_u32 s2, 64
	s_cbranch_scc1 .Leinv_skip_4
	buffer_inv sc1
	s_waitcnt vmcnt(0)
	s_getpc_b64 s[2:3]
